# B1 item queue: next-index atomic no longer waited right after issue
# speedup vs baseline: 1.1571x; 1.0012x over previous
.LBB0_326:
	s_and_saveexec_b64 s[0:1], s[38:39]
	s_cbranch_execz .LBB0_330
	s_mov_b64 s[28:29], exec
	v_mbcnt_lo_u32_b32 v0, s28, 0
	v_mbcnt_hi_u32_b32 v0, s29, v0
	v_cmp_eq_u32_e32 vcc, 0, v0
	s_and_saveexec_b64 s[20:21], vcc
	s_cbranch_execz .LBB0_329
	s_bcnt1_i32_b64 s2, s[28:29]
	v_mov_b32_e32 v1, s2
	global_atomic_add v205, v65, v1, s[76:77] sc0
.LBB0_329:
	s_or_b64 exec, exec, s[20:21]
.LBB0_330:
	s_or_b64 exec, exec, s[0:1]
	s_movk_i32 s0, 0x407
	v_cmp_lt_i32_e32 vcc, s0, v206
	s_and_saveexec_b64 s[0:1], vcc
	s_xor_b64 s[96:97], exec, s[0:1]
	s_cbranch_execz .LBB0_405
	s_movk_i32 s0, 0x447
	v_cmp_lt_u32_e32 vcc, s0, v206
	s_and_saveexec_b64 s[0:1], vcc
	s_xor_b64 s[56:57], exec, s[0:1]
	s_cbranch_execz .LBB0_364
	s_movk_i32 s0, 0x64b
	v_cmp_lt_u32_e32 vcc, s0, v206
	s_and_saveexec_b64 s[0:1], vcc
	s_xor_b64 s[0:1], exec, s[0:1]
	s_cbranch_execz .LBB0_334
	v_add_u32_e32 v48, 0xfffff9b4, v206
	v_lshrrev_b32_e32 v50, 6, v48
	v_bfe_u32 v51, v48, 4, 2
	v_lshl_add_u32 v0, v50, 2, s37
	v_or_b32_e32 v0, v0, v51
	v_ashrrev_i32_e32 v1, 31, v0
	v_readlane_b32 s20, v214, 37
	v_mov_b32_e32 v49, v133
	v_lshlrev_b64 v[0:1], 15, v[0:1]
	v_readlane_b32 s21, v214, 38
	s_nop 0
	v_lshlrev_b32_e32 v4, 4, v49
	v_lshl_add_u64 v[2:3], s[20:21], 0, v[0:1]
	v_readlane_b32 s20, v214, 39
	v_readlane_b32 s21, v214, 40
	v_and_b32_e32 v64, 0x70, v4
	v_lshl_add_u64 v[24:25], v[2:3], 0, v[64:65]
	v_lshl_add_u64 v[0:1], s[20:21], 0, v[0:1]
	v_add_u32_e32 v32, 0, v64
	v_and_b32_e32 v64, 0x1f0, v4
	v_ashrrev_i32_e32 v33, 3, v49
	v_lshl_add_u64 v[28:29], v[0:1], 0, v[64:65]
	v_lshlrev_b32_e32 v0, 6, v33
	v_ashrrev_i32_e32 v41, 5, v49
	v_add_u32_e32 v12, 0x200, v49
	v_ashrrev_i32_e32 v1, 31, v0
	v_lshlrev_b32_e32 v4, 8, v41
	v_ashrrev_i32_e32 v36, 3, v12
	v_lshl_add_u64 v[0:1], v[0:1], 1, v[24:25]
	v_ashrrev_i32_e32 v5, 31, v4
	v_lshlrev_b32_e32 v8, 6, v36
	v_ashrrev_i32_e32 v44, 5, v12
	v_add_u32_e32 v20, 0x400, v49
	s_barrier
	global_load_dwordx4 v[0:3], v[0:1], off
	v_lshl_add_u64 v[4:5], v[4:5], 1, v[28:29]
	v_ashrrev_i32_e32 v9, 31, v8
	v_lshlrev_b32_e32 v12, 8, v44
	v_ashrrev_i32_e32 v38, 3, v20
	global_load_dwordx4 v[4:7], v[4:5], off
	v_lshl_add_u64 v[8:9], v[8:9], 1, v[24:25]
	v_ashrrev_i32_e32 v13, 31, v12
	v_lshlrev_b32_e32 v16, 6, v38
	v_ashrrev_i32_e32 v46, 5, v20
	v_add_u32_e32 v30, 0x600, v49
	global_load_dwordx4 v[8:11], v[8:9], off
	v_lshl_add_u64 v[12:13], v[12:13], 1, v[28:29]
	v_ashrrev_i32_e32 v17, 31, v16
	v_lshlrev_b32_e32 v20, 8, v46
	v_ashrrev_i32_e32 v40, 3, v30
	global_load_dwordx4 v[12:15], v[12:13], off
	v_lshl_add_u64 v[16:17], v[16:17], 1, v[24:25]
	v_ashrrev_i32_e32 v21, 31, v20
	v_lshlrev_b32_e32 v26, 6, v40
	v_ashrrev_i32_e32 v52, 5, v30
	global_load_dwordx4 v[16:19], v[16:17], off
	v_lshl_add_u64 v[20:21], v[20:21], 1, v[28:29]
	v_ashrrev_i32_e32 v27, 31, v26
	v_lshlrev_b32_e32 v30, 8, v52
	global_load_dwordx4 v[20:23], v[20:21], off
	v_lshl_add_u64 v[24:25], v[26:27], 1, v[24:25]
	v_ashrrev_i32_e32 v31, 31, v30
	global_load_dwordx4 v[24:27], v[24:25], off
	v_lshl_add_u64 v[28:29], v[30:31], 1, v[28:29]
	global_load_dwordx4 v[28:31], v[28:29], off
	s_movk_i32 s22, 0x90
	v_mad_u64_u32 v[34:35], s[20:21], v33, s22, v[32:33]
	v_mad_u64_u32 v[36:37], s[20:21], v36, s22, v[32:33]
	v_mad_u64_u32 v[38:39], s[20:21], v38, s22, v[32:33]
	v_mad_u64_u32 v[32:33], s[20:21], v40, s22, v[32:33]
	v_add_u32_e32 v40, 0, v64
	v_mad_u64_u32 v[42:43], s[20:21], v41, s26, v[40:41]
	v_mad_u64_u32 v[44:45], s[20:21], v44, s26, v[40:41]
	v_mad_u64_u32 v[46:47], s[20:21], v46, s26, v[40:41]
	v_mad_u64_u32 v[40:41], s[20:21], v52, s26, v[40:41]
	v_and_b32_e32 v74, 15, v49
	v_readlane_b32 s20, v214, 12
	v_readlane_b32 s21, v214, 13
	v_bfe_u32 v71, v49, 4, 2
	v_lshlrev_b32_e32 v64, 7, v51
	s_movk_i32 s2, 0x1000
	s_movk_i32 s79, 0x90
	s_waitcnt vmcnt(7)
	ds_write_b128 v34, v[0:3]
	s_waitcnt vmcnt(6)
	ds_write_b128 v42, v[4:7] offset:36864
	s_waitcnt vmcnt(5)
	ds_write_b128 v36, v[8:11]
	s_waitcnt vmcnt(4)
	ds_write_b128 v44, v[12:15] offset:36864
	s_waitcnt vmcnt(3)
	ds_write_b128 v38, v[16:19]
	s_waitcnt vmcnt(2)
	ds_write_b128 v46, v[20:23] offset:36864
	s_waitcnt vmcnt(1)
	ds_write_b128 v32, v[24:27]
	s_waitcnt vmcnt(0)
	ds_write_b128 v40, v[28:31] offset:36864
	v_lshlrev_b32_e32 v1, 7, v48
	v_lshlrev_b32_e32 v0, 11, v50
	v_and_b32_e32 v1, 0x780, v1
	v_ashrrev_i32_e32 v2, 2, v49
	v_and_b32_e32 v2, -16, v2
	v_or3_b32 v0, v0, v1, v74
	v_add_u32_e32 v70, v0, v2
	v_mov_b64_e32 v[0:1], s[20:21]
	v_mad_i64_i32 v[0:1], s[20:21], v70, s83, v[0:1]
	v_lshlrev_b32_e32 v4, 4, v71
	v_mov_b32_e32 v5, v65
	v_lshl_add_u64 v[72:73], v[0:1], 0, v[64:65]
	v_lshl_add_u64 v[36:37], v[72:73], 0, v[4:5]
	v_add_co_u32_e32 v0, vcc, s2, v36
	s_waitcnt lgkmcnt(0)
	s_nop 0
	v_addc_co_u32_e32 v1, vcc, 0, v37, vcc
	s_barrier
	global_load_dwordx4 v[0:3], v[0:1], off offset:1280
	s_mov_b64 s[20:21], 0x1500
	v_lshl_add_u64 v[36:37], v[36:37], 0, s[20:21]
	global_load_dwordx4 v[66:69], v[36:37], off offset:64
	v_add_u32_e32 v75, 0, v4
	v_mad_u32_u24 v104, v74, s22, v75
	ds_read_b128 v[36:39], v104 offset:18432
	ds_read_b128 v[4:7], v104
	ds_read_b128 v[8:11], v104 offset:2304
	ds_read_b128 v[12:15], v104 offset:4608
	ds_read_b128 v[16:19], v104 offset:6912
	ds_read_b128 v[20:23], v104 offset:9216
	ds_read_b128 v[24:27], v104 offset:11520
	ds_read_b128 v[28:31], v104 offset:13824
	ds_read_b128 v[32:35], v104 offset:16128
	s_mov_b32 s20, 0xf149f2ca
	s_movk_i32 s73, 0x1000
	s_waitcnt vmcnt(1) lgkmcnt(8)
	v_mfma_f32_16x16x32_bf16 v[76:79], v[36:39], v[0:3], 0
	ds_read_b128 v[36:39], v104 offset:20736
	s_waitcnt lgkmcnt(0)
	v_mfma_f32_16x16x32_bf16 v[80:83], v[36:39], v[0:3], 0
	ds_read_b128 v[36:39], v104 offset:23040
	s_waitcnt lgkmcnt(0)
	v_mfma_f32_16x16x32_bf16 v[84:87], v[36:39], v[0:3], 0
	ds_read_b128 v[36:39], v104 offset:25344
	s_waitcnt lgkmcnt(0)
	v_mfma_f32_16x16x32_bf16 v[88:91], v[36:39], v[0:3], 0
	ds_read_b128 v[36:39], v104 offset:27648
	s_waitcnt lgkmcnt(0)
	v_mfma_f32_16x16x32_bf16 v[92:95], v[36:39], v[0:3], 0
	ds_read_b128 v[36:39], v104 offset:29952
	s_waitcnt lgkmcnt(0)
	v_mfma_f32_16x16x32_bf16 v[96:99], v[36:39], v[0:3], 0
	ds_read_b128 v[36:39], v104 offset:32256
	s_waitcnt lgkmcnt(0)
	v_mfma_f32_16x16x32_bf16 v[100:103], v[36:39], v[0:3], 0
	ds_read_b128 v[36:39], v104 offset:64
	v_mfma_f32_16x16x32_bf16 v[4:7], v[4:7], v[0:3], 0
	s_waitcnt vmcnt(0) lgkmcnt(0)
	v_mfma_f32_16x16x32_bf16 v[60:63], v[36:39], v[66:69], v[4:7]
	s_nop 5
	ds_read_b128 v[4:7], v104 offset:2368
	v_mfma_f32_16x16x32_bf16 v[8:11], v[8:11], v[0:3], 0
	s_waitcnt lgkmcnt(0)
	v_mfma_f32_16x16x32_bf16 v[56:59], v[4:7], v[66:69], v[8:11]
	ds_read_b128 v[4:7], v104 offset:4672
	v_mfma_f32_16x16x32_bf16 v[12:15], v[12:15], v[0:3], 0
	s_waitcnt lgkmcnt(0)
	v_mfma_f32_16x16x32_bf16 v[52:55], v[4:7], v[66:69], v[12:15]
	ds_read_b128 v[4:7], v104 offset:6976
	v_mfma_f32_16x16x32_bf16 v[16:19], v[16:19], v[0:3], 0
	s_waitcnt lgkmcnt(0)
	v_mfma_f32_16x16x32_bf16 v[48:51], v[4:7], v[66:69], v[16:19]
	ds_read_b128 v[4:7], v104 offset:9280
	v_mfma_f32_16x16x32_bf16 v[20:23], v[20:23], v[0:3], 0
	s_waitcnt lgkmcnt(0)
	v_mfma_f32_16x16x32_bf16 v[44:47], v[4:7], v[66:69], v[20:23]
	ds_read_b128 v[4:7], v104 offset:11584
	v_mfma_f32_16x16x32_bf16 v[24:27], v[24:27], v[0:3], 0
	s_waitcnt lgkmcnt(0)
	v_mfma_f32_16x16x32_bf16 v[40:43], v[4:7], v[66:69], v[24:27]
	ds_read_b128 v[4:7], v104 offset:13888
	v_mfma_f32_16x16x32_bf16 v[28:31], v[28:31], v[0:3], 0
	s_waitcnt lgkmcnt(0)
	v_mfma_f32_16x16x32_bf16 v[36:39], v[4:7], v[66:69], v[28:31]
	ds_read_b128 v[4:7], v104 offset:16192
	v_mfma_f32_16x16x32_bf16 v[32:35], v[32:35], v[0:3], 0
	s_waitcnt lgkmcnt(0)
	v_mfma_f32_16x16x32_bf16 v[32:35], v[4:7], v[66:69], v[32:35]
	ds_read_b128 v[4:7], v104 offset:18496
	s_waitcnt lgkmcnt(0)
	v_mfma_f32_16x16x32_bf16 v[28:31], v[4:7], v[66:69], v[76:79]
	ds_read_b128 v[4:7], v104 offset:20800
	s_nop 1
	ds_read_b128 v[76:79], v104 offset:34560
	s_waitcnt lgkmcnt(1)
	v_mfma_f32_16x16x32_bf16 v[24:27], v[4:7], v[66:69], v[80:83]
	ds_read_b128 v[4:7], v104 offset:23104
	s_waitcnt lgkmcnt(1)
	v_mfma_f32_16x16x32_bf16 v[0:3], v[76:79], v[0:3], 0
	ds_read_b128 v[76:79], v104 offset:34624
	s_waitcnt lgkmcnt(1)
	v_mfma_f32_16x16x32_bf16 v[20:23], v[4:7], v[66:69], v[84:87]
	ds_read_b128 v[4:7], v104 offset:25408
	s_waitcnt lgkmcnt(0)
	v_mfma_f32_16x16x32_bf16 v[16:19], v[4:7], v[66:69], v[88:91]
	ds_read_b128 v[4:7], v104 offset:27712
	s_waitcnt lgkmcnt(0)
	v_mfma_f32_16x16x32_bf16 v[12:15], v[4:7], v[66:69], v[92:95]
	ds_read_b128 v[4:7], v104 offset:30016
	s_waitcnt lgkmcnt(0)
	v_mfma_f32_16x16x32_bf16 v[8:11], v[4:7], v[66:69], v[96:99]
	ds_read_b128 v[4:7], v104 offset:32320
	s_waitcnt lgkmcnt(0)
	v_mfma_f32_16x16x32_bf16 v[4:7], v[4:7], v[66:69], v[100:103]
	v_mfma_f32_16x16x32_bf16 v[0:3], v[76:79], v[66:69], v[0:3]
	v_max_f32_e32 v66, v63, v63
	v_max_f32_e32 v67, v62, v62
	v_max_f32_e32 v66, v67, v66
	v_max_f32_e32 v67, v59, v59
	v_max_f32_e32 v68, v58, v58
	v_max_f32_e32 v67, v68, v67
	v_max3_f32 v66, v60, v61, v66
	v_max3_f32 v67, v56, v57, v67
	v_max3_f32 v66, v66, s20, v67
	v_max_f32_e32 v67, v55, v55
	v_max_f32_e32 v68, v54, v54
	v_max_f32_e32 v67, v68, v67
	v_max_f32_e32 v68, v51, v51
	v_max_f32_e32 v69, v50, v50
	v_max_f32_e32 v68, v69, v68
	v_max3_f32 v67, v52, v53, v67
	v_max3_f32 v68, v48, v49, v68
	v_max3_f32 v66, v66, v67, v68
	v_max_f32_e32 v67, v47, v47
	v_max_f32_e32 v68, v46, v46
	v_max_f32_e32 v67, v68, v67
	v_max_f32_e32 v68, v43, v43
	v_max_f32_e32 v69, v42, v42
	v_max_f32_e32 v68, v69, v68
	v_max3_f32 v67, v44, v45, v67
	v_max3_f32 v68, v40, v41, v68
	v_max3_f32 v66, v66, v67, v68
	v_max_f32_e32 v67, v39, v39
	v_max_f32_e32 v68, v38, v38
	v_max_f32_e32 v67, v68, v67
	v_max_f32_e32 v68, v35, v35
	v_max_f32_e32 v69, v34, v34
	v_max_f32_e32 v68, v69, v68
	v_max3_f32 v67, v36, v37, v67
	v_max3_f32 v68, v32, v33, v68
	v_max3_f32 v66, v66, v67, v68
	v_max_f32_e32 v67, v31, v31
	v_max_f32_e32 v68, v30, v30
	v_max_f32_e32 v67, v68, v67
	v_max_f32_e32 v68, v27, v27
	v_max_f32_e32 v69, v26, v26
	v_max_f32_e32 v68, v69, v68
	v_max3_f32 v67, v28, v29, v67
	v_max3_f32 v68, v24, v25, v68
	v_max3_f32 v66, v66, v67, v68
	v_max_f32_e32 v67, v23, v23
	v_max_f32_e32 v68, v22, v22
	v_max_f32_e32 v67, v68, v67
	v_max_f32_e32 v68, v19, v19
	v_max_f32_e32 v69, v18, v18
	v_max_f32_e32 v68, v69, v68
	v_max3_f32 v67, v20, v21, v67
	v_max3_f32 v68, v16, v17, v68
	v_max3_f32 v66, v66, v67, v68
	v_max_f32_e32 v67, v15, v15
	v_max_f32_e32 v68, v14, v14
	v_max_f32_e32 v67, v68, v67
	v_max_f32_e32 v68, v11, v11
	v_max_f32_e32 v69, v10, v10
	v_max_f32_e32 v68, v69, v68
	v_max3_f32 v67, v12, v13, v67
	v_max3_f32 v68, v8, v9, v68
	v_max3_f32 v66, v66, v67, v68
	v_max_f32_e32 v67, v7, v7
	v_max_f32_e32 v68, v6, v6
	v_max_f32_e32 v67, v68, v67
	v_max_f32_e32 v68, v3, v3
	v_max_f32_e32 v69, v2, v2
	v_max_f32_e32 v68, v69, v68
	v_max3_f32 v67, v4, v5, v67
	v_max3_f32 v68, v0, v1, v68
	v_max3_f32 v66, v66, v67, v68
	v_and_b32_e32 v68, 64, v192
	v_xor_b32_e32 v67, 16, v192
	v_add_u32_e32 v68, 64, v68
	v_cmp_lt_i32_e32 vcc, v67, v68
	s_mov_b64 s[20:21], 0x1700
	s_nop 0
	v_cndmask_b32_e32 v67, v192, v67, vcc
	v_lshlrev_b32_e32 v69, 2, v67
	ds_bpermute_b32 v67, v69, v66
	s_waitcnt lgkmcnt(0)
	v_max_f32_e32 v67, v67, v67
	v_max_f32_e32 v67, v66, v67
	v_xor_b32_e32 v66, 32, v192
	v_cmp_lt_i32_e32 vcc, v66, v68
	s_nop 1
	v_cndmask_b32_e32 v66, v192, v66, vcc
	v_lshlrev_b32_e32 v68, 2, v66
	ds_bpermute_b32 v76, v68, v67
	v_lshlrev_b32_e32 v66, 3, v71
	s_waitcnt lgkmcnt(0)
	v_max_f32_e32 v71, v76, v76
	v_max_f32_e32 v71, v67, v71
	v_sub_f32_e32 v60, v60, v71
	v_mul_f32_e32 v60, 0x3e000000, v60
	v_mul_f32_e32 v60, 0x3fb8aa3b, v60
	v_exp_f32_e32 v78, v60
	v_sub_f32_e32 v60, v61, v71
	v_sub_f32_e32 v56, v56, v71
	v_mul_f32_e32 v60, 0x3e000000, v60
	v_mul_f32_e32 v56, 0x3e000000, v56
	v_mul_f32_e32 v60, 0x3fb8aa3b, v60
	v_mul_f32_e32 v56, 0x3fb8aa3b, v56
	v_exp_f32_e32 v79, v60
	v_sub_f32_e32 v60, v62, v71
	v_exp_f32_e32 v80, v56
	v_sub_f32_e32 v56, v57, v71
	v_sub_f32_e32 v52, v52, v71
	v_mul_f32_e32 v60, 0x3e000000, v60
	v_mul_f32_e32 v56, 0x3e000000, v56
	v_mul_f32_e32 v52, 0x3e000000, v52
	v_mul_f32_e32 v60, 0x3fb8aa3b, v60
	v_mul_f32_e32 v56, 0x3fb8aa3b, v56
	v_mul_f32_e32 v52, 0x3fb8aa3b, v52
	v_exp_f32_e32 v62, v60
	v_sub_f32_e32 v60, v63, v71
	v_exp_f32_e32 v81, v56
	v_sub_f32_e32 v56, v58, v71
	v_exp_f32_e32 v94, v52
	v_sub_f32_e32 v52, v53, v71
	v_mul_f32_e32 v60, 0x3e000000, v60
	v_mul_f32_e32 v56, 0x3e000000, v56
	v_mul_f32_e32 v52, 0x3e000000, v52
	v_mul_f32_e32 v60, 0x3fb8aa3b, v60
	v_mul_f32_e32 v56, 0x3fb8aa3b, v56
	v_mul_f32_e32 v52, 0x3fb8aa3b, v52
	v_exp_f32_e32 v63, v60
	v_exp_f32_e32 v86, v56
	v_sub_f32_e32 v56, v59, v71
	v_exp_f32_e32 v95, v52
	v_sub_f32_e32 v52, v54, v71
	v_sub_f32_e32 v40, v40, v71
	v_mul_f32_e32 v56, 0x3e000000, v56
	v_mul_f32_e32 v52, 0x3e000000, v52
	v_sub_f32_e32 v48, v48, v71
	v_mul_f32_e32 v40, 0x3e000000, v40
	v_add_f32_e32 v60, v78, v79
	v_mul_f32_e32 v56, 0x3fb8aa3b, v56
	v_mul_f32_e32 v52, 0x3fb8aa3b, v52
	v_mul_f32_e32 v48, 0x3e000000, v48
	v_mul_f32_e32 v40, 0x3fb8aa3b, v40
	v_add_f32_e32 v60, v62, v60
	v_exp_f32_e32 v59, v56
	v_exp_f32_e32 v98, v52
	v_sub_f32_e32 v52, v55, v71
	v_mul_f32_e32 v48, 0x3fb8aa3b, v48
	v_exp_f32_e32 v103, v40
	v_sub_f32_e32 v40, v41, v71
	v_add_f32_e32 v61, v63, v60
	v_mul_f32_e32 v52, 0x3e000000, v52
	v_exp_f32_e32 v60, v48
	v_sub_f32_e32 v48, v49, v71
	v_mul_f32_e32 v40, 0x3e000000, v40
	v_add_f32_e32 v56, v80, v81
	v_mul_f32_e32 v52, 0x3fb8aa3b, v52
	v_mul_f32_e32 v48, 0x3e000000, v48
	v_mul_f32_e32 v40, 0x3fb8aa3b, v40
	v_add_f32_e32 v56, v86, v56
	v_exp_f32_e32 v99, v52
	v_mul_f32_e32 v48, 0x3fb8aa3b, v48
	v_exp_f32_e32 v104, v40
	v_sub_f32_e32 v40, v42, v71
	v_add_f32_e32 v53, v59, v56
	v_exp_f32_e32 v56, v48
	v_sub_f32_e32 v48, v50, v71
	v_mul_f32_e32 v40, 0x3e000000, v40
	v_add_f32_e32 v52, v94, v95
	v_mul_f32_e32 v48, 0x3e000000, v48
	v_sub_f32_e32 v44, v44, v71
	v_mul_f32_e32 v40, 0x3fb8aa3b, v40
	v_add_f32_e32 v52, v98, v52
	v_mul_f32_e32 v48, 0x3fb8aa3b, v48
	v_mul_f32_e32 v44, 0x3e000000, v44
	v_exp_f32_e32 v105, v40
	v_sub_f32_e32 v40, v43, v71
	v_add_f32_e32 v55, v99, v52
	v_exp_f32_e32 v52, v48
	v_sub_f32_e32 v48, v51, v71
	v_mul_f32_e32 v44, 0x3fb8aa3b, v44
	v_mul_f32_e32 v40, 0x3e000000, v40
	v_mul_f32_e32 v48, 0x3e000000, v48
	v_exp_f32_e32 v100, v44
	v_sub_f32_e32 v44, v45, v71
	v_mul_f32_e32 v40, 0x3fb8aa3b, v40
	v_mul_f32_e32 v48, 0x3fb8aa3b, v48
	v_mul_f32_e32 v44, 0x3e000000, v44
	v_exp_f32_e32 v106, v40
	v_exp_f32_e32 v54, v48
	v_mul_f32_e32 v44, 0x3fb8aa3b, v44
	v_sub_f32_e32 v32, v32, v71
	v_mov_b32_e32 v57, v65
	v_exp_f32_e32 v45, v44
	v_sub_f32_e32 v44, v46, v71
	v_add_f32_e32 v40, v103, v104
	v_mul_f32_e32 v32, 0x3e000000, v32
	v_pk_add_f32 v[48:49], v[60:61], v[56:57]
	v_mul_f32_e32 v44, 0x3e000000, v44
	v_add_f32_e32 v40, v105, v40
	v_mul_f32_e32 v32, 0x3fb8aa3b, v32
	v_pk_add_f32 v[48:49], v[52:53], v[48:49]
	v_mul_f32_e32 v44, 0x3fb8aa3b, v44
	v_add_f32_e32 v43, v106, v40
	v_exp_f32_e32 v40, v32
	v_sub_f32_e32 v32, v33, v71
	v_pk_add_f32 v[48:49], v[54:55], v[48:49]
	v_exp_f32_e32 v101, v44
	v_sub_f32_e32 v44, v47, v71
	v_mul_f32_e32 v32, 0x3e000000, v32
	v_pk_add_f32 v[48:49], v[48:49], v[48:49] op_sel_hi:[0,1]
	v_mul_f32_e32 v44, 0x3e000000, v44
	v_mul_f32_e32 v32, 0x3fb8aa3b, v32
	v_mul_f32_e32 v44, 0x3fb8aa3b, v44
	v_sub_f32_e32 v36, v36, v71
	v_exp_f32_e32 v48, v32
	v_sub_f32_e32 v32, v34, v71
	v_sub_f32_e32 v24, v24, v71
	v_exp_f32_e32 v102, v44
	v_mul_f32_e32 v36, 0x3e000000, v36
	v_mul_f32_e32 v32, 0x3e000000, v32
	v_mul_f32_e32 v24, 0x3e000000, v24
	v_mul_f32_e32 v36, 0x3fb8aa3b, v36
	v_mul_f32_e32 v32, 0x3fb8aa3b, v32
	v_mul_f32_e32 v24, 0x3fb8aa3b, v24
	v_add_f32_e32 v44, v100, v45
	v_exp_f32_e32 v57, v36
	v_sub_f32_e32 v36, v37, v71
	v_exp_f32_e32 v42, v32
	v_sub_f32_e32 v32, v35, v71
	v_exp_f32_e32 v47, v24
	v_sub_f32_e32 v24, v25, v71
	v_add_f32_e32 v44, v101, v44
	v_mul_f32_e32 v36, 0x3e000000, v36
	v_mul_f32_e32 v32, 0x3e000000, v32
	v_sub_f32_e32 v28, v28, v71
	v_mul_f32_e32 v24, 0x3e000000, v24
	v_add_f32_e32 v41, v102, v44
	v_mul_f32_e32 v36, 0x3fb8aa3b, v36
	v_mul_f32_e32 v32, 0x3fb8aa3b, v32
	v_mul_f32_e32 v28, 0x3e000000, v28
	v_mul_f32_e32 v24, 0x3fb8aa3b, v24
	v_exp_f32_e32 v58, v36
	v_sub_f32_e32 v36, v38, v71
	v_exp_f32_e32 v34, v32
	v_pk_add_f32 v[32:33], v[40:41], v[48:49]
	v_mul_f32_e32 v28, 0x3fb8aa3b, v28
	v_exp_f32_e32 v49, v24
	v_sub_f32_e32 v24, v26, v71
	v_mul_f32_e32 v36, 0x3e000000, v36
	v_pk_add_f32 v[32:33], v[42:43], v[32:33]
	v_exp_f32_e32 v43, v28
	v_sub_f32_e32 v28, v29, v71
	v_mul_f32_e32 v24, 0x3e000000, v24
	v_mul_f32_e32 v36, 0x3fb8aa3b, v36
	v_mul_f32_e32 v28, 0x3e000000, v28
	v_mul_f32_e32 v24, 0x3fb8aa3b, v24
	v_exp_f32_e32 v53, v36
	v_sub_f32_e32 v36, v39, v71
	v_mul_f32_e32 v28, 0x3fb8aa3b, v28
	v_exp_f32_e32 v50, v24
	v_sub_f32_e32 v24, v27, v71
	v_mul_f32_e32 v36, 0x3e000000, v36
	v_exp_f32_e32 v46, v28
	v_sub_f32_e32 v28, v30, v71
	v_mul_f32_e32 v24, 0x3e000000, v24
	v_mul_f32_e32 v36, 0x3fb8aa3b, v36
	v_mul_f32_e32 v28, 0x3e000000, v28
	v_sub_f32_e32 v29, v31, v71
	v_mul_f32_e32 v24, 0x3fb8aa3b, v24
	v_exp_f32_e32 v55, v36
	v_mul_f32_e32 v28, 0x3fb8aa3b, v28
	v_mul_f32_e32 v29, 0x3e000000, v29
	v_exp_f32_e32 v51, v24
	v_exp_f32_e32 v28, v28
	v_mul_f32_e32 v29, 0x3fb8aa3b, v29
	v_sub_f32_e32 v16, v16, v71
	v_add_f32_e32 v36, v57, v58
	v_exp_f32_e32 v29, v29
	v_add_f32_e32 v24, v47, v49
	v_mul_f32_e32 v16, 0x3e000000, v16
	v_add_f32_e32 v36, v53, v36
	v_add_f32_e32 v24, v50, v24
	v_sub_f32_e32 v21, v21, v71
	v_mul_f32_e32 v16, 0x3fb8aa3b, v16
	v_add_f32_e32 v35, v55, v36
	v_add_f32_e32 v30, v43, v46
	v_add_f32_e32 v27, v51, v24
	v_mul_f32_e32 v21, 0x3e000000, v21
	v_exp_f32_e32 v24, v16
	v_sub_f32_e32 v16, v17, v71
	v_pk_add_f32 v[32:33], v[34:35], v[32:33]
	v_add_f32_e32 v30, v28, v30
	v_mul_f32_e32 v21, 0x3fb8aa3b, v21
	v_mul_f32_e32 v16, 0x3e000000, v16
	v_pk_add_f32 v[32:33], v[32:33], v[32:33] op_sel_hi:[0,1]
	v_add_f32_e32 v25, v29, v30
	v_exp_f32_e32 v30, v21
	v_sub_f32_e32 v21, v22, v71
	v_mul_f32_e32 v16, 0x3fb8aa3b, v16
	v_sub_f32_e32 v20, v20, v71
	v_mul_f32_e32 v21, 0x3e000000, v21
	v_exp_f32_e32 v32, v16
	v_sub_f32_e32 v16, v18, v71
	v_mul_f32_e32 v20, 0x3e000000, v20
	v_mul_f32_e32 v21, 0x3fb8aa3b, v21
	v_mul_f32_e32 v16, 0x3e000000, v16
	v_mul_f32_e32 v20, 0x3fb8aa3b, v20
	v_exp_f32_e32 v22, v21
	v_sub_f32_e32 v21, v23, v71
	v_mul_f32_e32 v16, 0x3fb8aa3b, v16
	v_exp_f32_e32 v20, v20
	v_mul_f32_e32 v21, 0x3e000000, v21
	v_exp_f32_e32 v26, v16
	v_sub_f32_e32 v16, v19, v71
	v_mul_f32_e32 v21, 0x3fb8aa3b, v21
	v_mul_f32_e32 v16, 0x3e000000, v16
	v_exp_f32_e32 v23, v21
	v_mul_f32_e32 v16, 0x3fb8aa3b, v16
	v_exp_f32_e32 v16, v16
	v_add_f32_e32 v21, v20, v30
	v_sub_f32_e32 v12, v12, v71
	v_add_f32_e32 v21, v22, v21
	v_pk_add_f32 v[18:19], v[24:25], v[32:33]
	v_mul_f32_e32 v12, 0x3e000000, v12
	v_add_f32_e32 v17, v23, v21
	v_pk_add_f32 v[18:19], v[26:27], v[18:19]
	v_mul_f32_e32 v12, 0x3fb8aa3b, v12
	v_pk_add_f32 v[36:37], v[16:17], v[18:19]
	v_exp_f32_e32 v18, v12
	v_sub_f32_e32 v12, v13, v71
	v_mul_f32_e32 v12, 0x3e000000, v12
	v_mul_f32_e32 v12, 0x3fb8aa3b, v12
	v_exp_f32_e32 v19, v12
	v_sub_f32_e32 v12, v14, v71
	v_mul_f32_e32 v12, 0x3e000000, v12
	v_sub_f32_e32 v8, v8, v71
	v_mul_f32_e32 v12, 0x3fb8aa3b, v12
	v_mul_f32_e32 v8, 0x3e000000, v8
	v_exp_f32_e32 v25, v12
	v_sub_f32_e32 v12, v15, v71
	v_mul_f32_e32 v8, 0x3fb8aa3b, v8
	v_mul_f32_e32 v12, 0x3e000000, v12
	v_exp_f32_e32 v33, v8
	v_sub_f32_e32 v8, v9, v71
	v_sub_u32_e32 v9, v75, v66
	v_mul_f32_e32 v12, 0x3fb8aa3b, v12
	v_mad_u32_u24 v9, v74, s26, v9
	v_exp_f32_e32 v27, v12
	v_pk_add_f32 v[12:13], v[36:37], v[36:37] op_sel_hi:[0,1]
	v_add_u32_e32 v39, 0x9000, v9
	v_add_u32_e32 v31, 0xb000, v9
	v_add_u32_e32 v35, 0xd000, v9
	v_add_u32_e32 v37, 0xf000, v9
	ds_read2_b64 v[74:77], v39 offset1:4
	ds_read2_b64 v[82:85], v31 offset0:32 offset1:36
	v_cvt_pk_bf16_f32 v80, v80, v81
	v_cvt_pk_bf16_f32 v81, v86, v59
	ds_read2_b64 v[86:89], v35 offset0:64 offset1:68
	ds_read2_b64 v[90:93], v37 offset0:96 offset1:100
	v_mul_f32_e32 v8, 0x3e000000, v8
	v_mul_f32_e32 v8, 0x3fb8aa3b, v8
	v_exp_f32_e32 v36, v8
	v_sub_f32_e32 v8, v10, v71
	v_mul_f32_e32 v8, 0x3e000000, v8
	v_mul_f32_e32 v8, 0x3fb8aa3b, v8
	v_add_f32_e32 v12, v18, v19
	v_exp_f32_e32 v41, v8
	v_sub_f32_e32 v8, v11, v71
	v_add_f32_e32 v12, v25, v12
	v_cvt_pk_bf16_f32 v78, v78, v79
	v_cvt_pk_bf16_f32 v79, v62, v63
	v_mul_f32_e32 v8, 0x3e000000, v8
	v_add_f32_e32 v15, v27, v12
	s_waitcnt lgkmcnt(3)
	v_mfma_f32_16x16x32_bf16 v[74:77], v[74:77], v[78:81], 0
	v_mul_f32_e32 v12, 0x3fb8aa3b, v8
	v_sub_f32_e32 v4, v4, v71
	v_mul_f32_e32 v4, 0x3e000000, v4
	s_waitcnt lgkmcnt(2)
	v_mfma_f32_16x16x32_bf16 v[82:85], v[82:85], v[78:81], 0
	v_mul_f32_e32 v4, 0x3fb8aa3b, v4
	v_exp_f32_e32 v38, v4
	v_sub_f32_e32 v4, v5, v71
	s_waitcnt lgkmcnt(1)
	v_mfma_f32_16x16x32_bf16 v[8:11], v[86:89], v[78:81], 0
	ds_read2_b64 v[86:89], v39 offset0:8 offset1:12
	v_mul_f32_e32 v4, 0x3e000000, v4
	v_mul_f32_e32 v4, 0x3fb8aa3b, v4
	s_waitcnt lgkmcnt(1)
	v_mfma_f32_16x16x32_bf16 v[78:81], v[90:93], v[78:81], 0
	v_cvt_pk_bf16_f32 v92, v60, v56
	ds_read2_b64 v[60:63], v35 offset0:72 offset1:76
	v_cvt_pk_bf16_f32 v90, v94, v95
	ds_read2_b64 v[94:97], v31 offset0:40 offset1:44
	v_cvt_pk_bf16_f32 v91, v98, v99
	v_cvt_pk_bf16_f32 v93, v52, v54
	v_exp_f32_e32 v44, v12
	s_waitcnt lgkmcnt(2)
	v_mfma_f32_16x16x32_bf16 v[74:77], v[86:89], v[90:93], v[74:77]
	ds_read2_b64 v[86:89], v37 offset0:104 offset1:108
	v_add_f32_e32 v12, v33, v36
	v_add_f32_e32 v12, v41, v12
	s_waitcnt lgkmcnt(2)
	v_mfma_f32_16x16x32_bf16 v[8:11], v[60:63], v[90:93], v[8:11]
	ds_read2_b64 v[60:63], v39 offset0:16 offset1:20
	v_sub_f32_e32 v0, v0, v71
	v_add_f32_e32 v17, v44, v12
	s_waitcnt lgkmcnt(2)
	v_mfma_f32_16x16x32_bf16 v[82:85], v[94:97], v[90:93], v[82:85]
	ds_read2_b64 v[94:97], v35 offset0:80 offset1:84
	v_mul_f32_e32 v0, 0x3e000000, v0
	v_mov_b32_e32 v67, v65
	s_waitcnt lgkmcnt(2)
	v_mfma_f32_16x16x32_bf16 v[78:81], v[86:89], v[90:93], v[78:81]
	v_cvt_pk_bf16_f32 v86, v100, v45
	ds_read2_b64 v[90:93], v31 offset0:48 offset1:52
	v_cvt_pk_bf16_f32 v87, v101, v102
	v_cvt_pk_bf16_f32 v88, v103, v104
	v_cvt_pk_bf16_f32 v89, v105, v106
	v_exp_f32_e32 v45, v4
	s_waitcnt lgkmcnt(2)
	v_mfma_f32_16x16x32_bf16 v[60:63], v[60:63], v[86:89], v[74:77]
	v_sub_f32_e32 v4, v6, v71
	v_mul_f32_e32 v4, 0x3e000000, v4
	v_mul_f32_e32 v4, 0x3fb8aa3b, v4
	ds_read2_b64 v[74:77], v37 offset0:112 offset1:116
	s_waitcnt lgkmcnt(1)
	v_mfma_f32_16x16x32_bf16 v[82:85], v[90:93], v[86:89], v[82:85]
	v_exp_f32_e32 v52, v4
	v_sub_f32_e32 v4, v7, v71
	v_mul_f32_e32 v12, 0x3e000000, v4
	v_mfma_f32_16x16x32_bf16 v[8:11], v[94:97], v[86:89], v[8:11]
	v_mul_f32_e32 v12, 0x3fb8aa3b, v12
	v_mul_f32_e32 v0, 0x3fb8aa3b, v0
	v_cvt_pk_bf16_f32 v54, v57, v58
	s_waitcnt lgkmcnt(0)
	v_mfma_f32_16x16x32_bf16 v[74:77], v[74:77], v[86:89], v[78:81]
	ds_read2_b64 v[86:89], v35 offset0:88 offset1:92
	v_cvt_pk_bf16_f32 v55, v53, v55
	v_cvt_pk_bf16_f32 v56, v40, v48
	v_cvt_pk_bf16_f32 v57, v42, v34
	v_exp_f32_e32 v34, v12
	s_nop 0
	ds_read2_b64 v[78:81], v31 offset0:56 offset1:60
	s_waitcnt lgkmcnt(0)
	v_mfma_f32_16x16x32_bf16 v[78:81], v[78:81], v[54:57], v[82:85]
	v_add_f32_e32 v12, v38, v45
	v_exp_f32_e32 v14, v0
	v_sub_f32_e32 v0, v1, v71
	v_mfma_f32_16x16x32_bf16 v[82:85], v[86:89], v[54:57], v[8:11]
	v_cvt_pk_bf16_f32 v11, v50, v51
	v_lshl_add_u64 v[50:51], v[72:73], 0, v[66:67]
	ds_read2_b64 v[90:93], v39 offset0:24 offset1:28
	ds_read2_b64 v[4:7], v37 offset0:120 offset1:124
	v_add_f32_e32 v8, v52, v12
	v_mul_f32_e32 v12, 0x3e000000, v0
	v_add_co_u32_e32 v0, vcc, s2, v50
	v_cvt_pk_bf16_f32 v9, v28, v29
	s_waitcnt lgkmcnt(1)
	v_mfma_f32_16x16x32_bf16 v[58:61], v[90:93], v[54:57], v[60:63]
	v_addc_co_u32_e32 v1, vcc, 0, v51, vcc
	global_load_dwordx2 v[28:29], v[0:1], off offset:1792
	s_waitcnt lgkmcnt(0)
	v_mfma_f32_16x16x32_bf16 v[4:7], v[4:7], v[54:57], v[74:77]
	ds_read2_b64 v[54:57], v31 offset0:64 offset1:68
	ds_read2_b64 v[86:89], v39 offset0:32 offset1:36
	v_add_f32_e32 v21, v34, v8
	v_cvt_pk_bf16_f32 v8, v43, v46
	v_cvt_pk_bf16_f32 v10, v47, v49
	ds_read2_b64 v[46:49], v35 offset0:96 offset1:100
	s_waitcnt lgkmcnt(2)
	v_mfma_f32_16x16x32_bf16 v[54:57], v[54:57], v[8:11], v[78:81]
	ds_read2_b64 v[74:77], v37 offset0:128 offset1:132
	s_nop 1
	ds_read2_b64 v[78:81], v39 offset0:40 offset1:44
	v_mul_f32_e32 v0, 0x3fb8aa3b, v12
	s_waitcnt lgkmcnt(3)
	v_mfma_f32_16x16x32_bf16 v[58:61], v[86:89], v[8:11], v[58:61]
	v_exp_f32_e32 v12, v0
	v_sub_f32_e32 v0, v2, v71
	v_mul_f32_e32 v0, 0x3e000000, v0
	s_waitcnt lgkmcnt(2)
	v_mfma_f32_16x16x32_bf16 v[46:49], v[46:49], v[8:11], v[82:85]
	v_mul_f32_e32 v0, 0x3fb8aa3b, v0
	s_mov_b32 s2, 0x4580000
	s_waitcnt lgkmcnt(1)
	v_mfma_f32_16x16x32_bf16 v[4:7], v[74:77], v[8:11], v[4:7]
	v_cvt_pk_bf16_f32 v8, v20, v30
	ds_read2_b64 v[72:75], v31 offset0:72 offset1:76
	v_cvt_pk_bf16_f32 v9, v22, v23
	v_cvt_pk_bf16_f32 v10, v24, v32
	v_cvt_pk_bf16_f32 v11, v26, v16
	ds_read2_b64 v[82:85], v35 offset0:104 offset1:108
	s_waitcnt lgkmcnt(2)
	v_mfma_f32_16x16x32_bf16 v[58:61], v[78:81], v[8:11], v[58:61]
	ds_read2_b64 v[76:79], v37 offset0:136 offset1:140
	v_exp_f32_e32 v16, v0
	v_sub_f32_e32 v0, v3, v71
	s_waitcnt lgkmcnt(2)
	v_mfma_f32_16x16x32_bf16 v[54:57], v[72:75], v[8:11], v[54:57]
	v_mul_f32_e32 v20, 0x3e000000, v0
	ds_read2_b64 v[72:75], v39 offset0:48 offset1:52
	v_cvt_pk_bf16_f32 v32, v14, v12
	s_waitcnt lgkmcnt(2)
	v_mfma_f32_16x16x32_bf16 v[46:49], v[82:85], v[8:11], v[46:49]
	v_cvt_pk_bf16_f32 v30, v38, v45
	v_ashrrev_i32_e32 v71, 31, v70
	s_waitcnt lgkmcnt(1)
	v_mfma_f32_16x16x32_bf16 v[0:3], v[76:79], v[8:11], v[4:7]
	ds_read2_b64 v[8:11], v31 offset0:80 offset1:84
	v_cvt_pk_bf16_f32 v4, v18, v19
	v_mul_f32_e32 v18, 0x3fb8aa3b, v20
	v_exp_f32_e32 v20, v18
	v_pk_add_f32 v[18:19], v[14:15], v[12:13]
	v_cvt_pk_bf16_f32 v5, v25, v27
	v_cvt_pk_bf16_f32 v6, v33, v36
	v_cvt_pk_bf16_f32 v7, v41, v44
	ds_read2_b64 v[40:43], v35 offset0:112 offset1:116
	s_waitcnt lgkmcnt(1)
	v_mfma_f32_16x16x32_bf16 v[8:11], v[8:11], v[4:7], v[54:57]
	v_add_f32_e64 v18, v16, v18
	v_add_f32_e64 v19, v17, v19
	ds_read2_b64 v[12:15], v35 offset0:120 offset1:124
	v_pk_add_f32 v[18:19], v[20:21], v[18:19]
	ds_read2_b64 v[54:57], v37 offset0:144 offset1:148
	v_add_f32_e32 v17, v18, v19
	v_lshl_add_u64 v[18:19], v[50:51], 0, s[20:21]
	global_load_dwordx2 v[22:23], v[18:19], off offset:32
	ds_bpermute_b32 v21, v69, v17
	v_mfma_f32_16x16x32_bf16 v[24:27], v[72:75], v[4:7], v[58:61]
	v_cvt_pk_bf16_f32 v33, v16, v20
	s_waitcnt lgkmcnt(0)
	v_add_f32_e32 v16, v17, v21
	v_mfma_f32_16x16x32_bf16 v[40:43], v[40:43], v[4:7], v[46:49]
	ds_bpermute_b32 v17, v68, v16
	s_waitcnt lgkmcnt(0)
	v_add_f32_e32 v16, v16, v17
	v_mfma_f32_16x16x32_bf16 v[0:3], v[54:57], v[4:7], v[0:3]
	ds_read2_b64 v[4:7], v31 offset0:88 offset1:92
	v_cvt_pk_bf16_f32 v31, v52, v34
	ds_read2_b64 v[46:49], v39 offset0:56 offset1:60
	s_waitcnt lgkmcnt(1)
	v_mfma_f32_16x16x32_bf16 v[8:11], v[4:7], v[30:33], v[8:11]
	ds_read2_b64 v[34:37], v37 offset0:152 offset1:156
	v_mfma_f32_16x16x32_bf16 v[4:7], v[12:15], v[30:33], v[40:43]
	v_div_scale_f32 v12, s[20:21], v16, v16, 1.0
	v_rcp_f32_e32 v13, v12
	s_waitcnt lgkmcnt(1)
	v_mfma_f32_16x16x32_bf16 v[24:27], v[46:49], v[30:33], v[24:27]
	s_mov_b64 s[20:21], 0x4580600
	v_fma_f32 v14, -v12, v13, 1.0
	v_fmac_f32_e32 v13, v14, v13
	v_div_scale_f32 v14, vcc, 1.0, v16, 1.0
	v_mul_f32_e32 v15, v14, v13
	v_fma_f32 v17, -v12, v15, v14
	v_fmac_f32_e32 v15, v17, v13
	v_fma_f32 v12, -v12, v15, v14
	v_div_fmas_f32 v12, v12, v13, v15
	global_load_dwordx2 v[14:15], v[18:19], off offset:64
	v_div_fixup_f32 v12, v12, v16, 1.0
	v_lshlrev_b64 v[16:17], 11, v[70:71]
	v_lshl_add_u64 v[16:17], s[94:95], 0, v[16:17]
	v_lshl_add_u64 v[20:21], v[16:17], 0, v[64:65]
	s_waitcnt vmcnt(2)
	v_lshlrev_b32_e32 v17, 16, v28
	v_mul_f32_e32 v13, 0xbfb8aa3b, v17
	v_exp_f32_e32 v13, v13
	s_waitcnt lgkmcnt(0)
	v_mfma_f32_16x16x32_bf16 v[0:3], v[34:37], v[30:33], v[0:3]
	v_and_b32_e32 v31, 0xffff0000, v28
	v_mul_f32_e32 v16, 0xbfb8aa3b, v31
	v_add_f32_e32 v13, 1.0, v13
	v_rcp_f32_e32 v13, v13
	v_exp_f32_e32 v28, v16
	v_mov_b32_e32 v16, v24
	v_lshlrev_b32_e32 v33, 16, v29
	v_pk_mul_f32 v[16:17], v[12:13], v[16:17]
	v_add_f32_e32 v13, 1.0, v28
	v_mul_f32_e32 v24, v16, v17
	v_mul_f32_e32 v16, 0xbfb8aa3b, v33
	v_rcp_f32_e32 v13, v13
	v_exp_f32_e32 v28, v16
	v_mov_b32_e32 v30, v25
	v_and_b32_e32 v29, 0xffff0000, v29
	v_pk_mul_f32 v[16:17], v[12:13], v[30:31]
	v_add_f32_e32 v13, 1.0, v28
	v_mul_f32_e32 v16, v16, v17
	v_rcp_f32_e32 v13, v13
	v_mul_f32_e32 v17, 0xbfb8aa3b, v29
	v_exp_f32_e32 v25, v17
	v_mov_b32_e32 v32, v26
	v_cvt_pk_bf16_f32 v24, v24, v16
	v_pk_mul_f32 v[16:17], v[12:13], v[32:33]
	v_add_f32_e32 v13, 1.0, v25
	v_mul_f32_e32 v25, v16, v17
	global_load_dwordx2 v[16:17], v[18:19], off offset:96
	v_rcp_f32_e32 v13, v13
	v_mov_b32_e32 v28, v27
	s_waitcnt vmcnt(2)
	v_lshlrev_b32_e32 v27, 16, v22
	v_lshl_add_u64 v[20:21], v[20:21], 0, v[66:67]
	v_pk_mul_f32 v[18:19], v[12:13], v[28:29]
	v_mov_b32_e32 v26, v8
	v_mul_f32_e32 v13, v18, v19
	v_cvt_pk_bf16_f32 v25, v25, v13
	v_mul_f32_e32 v13, 0xbfb8aa3b, v27
	v_lshl_add_u64 v[18:19], v[20:21], 0, s[20:21]
	v_add_co_u32_e32 v20, vcc, s2, v20
	v_exp_f32_e32 v13, v13
	s_nop 0
	v_addc_co_u32_e32 v21, vcc, 0, v21, vcc
	global_store_dwordx2 v[20:21], v[24:25], off offset:1536
	v_and_b32_e32 v21, 0xffff0000, v22
	v_mul_f32_e32 v20, 0xbfb8aa3b, v21
	v_add_f32_e32 v13, 1.0, v13
	v_exp_f32_e32 v20, v20
	v_rcp_f32_e32 v13, v13
	v_lshlrev_b32_e32 v25, 16, v23
	v_and_b32_e32 v23, 0xffff0000, v23
	v_add_f32_e32 v8, 1.0, v20
	v_pk_mul_f32 v[26:27], v[12:13], v[26:27]
	v_rcp_f32_e32 v13, v8
	v_mul_f32_e32 v8, 0xbfb8aa3b, v25
	v_exp_f32_e32 v22, v8
	v_mov_b32_e32 v20, v9
	v_pk_mul_f32 v[8:9], v[12:13], v[20:21]
	v_mul_f32_e32 v20, 0xbfb8aa3b, v23
	v_add_f32_e32 v13, 1.0, v22
	v_exp_f32_e32 v20, v20
	v_rcp_f32_e32 v13, v13
	v_mov_b32_e32 v24, v10
	v_mul_f32_e32 v21, v8, v9
	v_add_f32_e32 v10, 1.0, v20
	v_pk_mul_f32 v[8:9], v[12:13], v[24:25]
	v_rcp_f32_e32 v13, v10
	v_mov_b32_e32 v22, v11
	v_mul_f32_e32 v20, v8, v9
	v_mul_f32_e32 v26, v26, v27
	v_pk_mul_f32 v[8:9], v[12:13], v[22:23]
	v_cvt_pk_bf16_f32 v10, v26, v21
	s_waitcnt vmcnt(2)
	v_lshlrev_b32_e32 v21, 16, v15
	v_mul_f32_e32 v8, v8, v9
	v_lshlrev_b32_e32 v9, 16, v14
	v_cvt_pk_bf16_f32 v11, v20, v8
	v_mul_f32_e32 v8, 0xbfb8aa3b, v9
	v_exp_f32_e32 v8, v8
	global_store_dwordx2 v[18:19], v[10:11], off offset:32
	v_and_b32_e32 v11, 0xffff0000, v14
	v_and_b32_e32 v15, 0xffff0000, v15
	v_add_f32_e32 v8, 1.0, v8
	v_rcp_f32_e32 v13, v8
	v_mul_f32_e32 v8, 0xbfb8aa3b, v11
	v_exp_f32_e32 v10, v8
	v_mov_b32_e32 v8, v4
	v_pk_mul_f32 v[8:9], v[12:13], v[8:9]
	v_mov_b32_e32 v20, v6
	v_add_f32_e32 v4, 1.0, v10
	v_rcp_f32_e32 v13, v4
	v_mul_f32_e32 v4, 0xbfb8aa3b, v21
	v_exp_f32_e32 v14, v4
	v_mul_f32_e32 v8, v8, v9
	v_mov_b32_e32 v10, v5
	v_pk_mul_f32 v[4:5], v[12:13], v[10:11]
	v_add_f32_e32 v9, 1.0, v14
	v_rcp_f32_e32 v13, v9
	v_mul_f32_e32 v9, 0xbfb8aa3b, v15
	v_exp_f32_e32 v9, v9
	v_mul_f32_e32 v10, v4, v5
	v_pk_mul_f32 v[4:5], v[12:13], v[20:21]
	v_mov_b32_e32 v14, v7
	v_add_f32_e32 v6, 1.0, v9
	v_rcp_f32_e32 v13, v6
	v_cvt_pk_bf16_f32 v6, v8, v10
	v_mul_f32_e32 v8, v4, v5
	v_mov_b32_e32 v10, v3
	v_pk_mul_f32 v[4:5], v[12:13], v[14:15]
	s_waitcnt vmcnt(2)
	v_lshlrev_b32_e32 v9, 16, v17
	v_mul_f32_e32 v4, v4, v5
	v_lshlrev_b32_e32 v5, 16, v16
	v_cvt_pk_bf16_f32 v7, v8, v4
	v_mul_f32_e32 v4, 0xbfb8aa3b, v5
	v_exp_f32_e32 v4, v4
	global_store_dwordx2 v[18:19], v[6:7], off offset:64
	v_and_b32_e32 v7, 0xffff0000, v16
	v_and_b32_e32 v11, 0xffff0000, v17
	v_add_f32_e32 v4, 1.0, v4
	v_rcp_f32_e32 v13, v4
	v_mul_f32_e32 v4, 0xbfb8aa3b, v7
	v_exp_f32_e32 v6, v4
	v_mov_b32_e32 v4, v0
	v_pk_mul_f32 v[4:5], v[12:13], v[4:5]
	v_add_f32_e32 v0, 1.0, v6
	v_rcp_f32_e32 v13, v0
	v_mul_f32_e32 v0, 0xbfb8aa3b, v9
	v_exp_f32_e32 v8, v0
	v_mul_f32_e32 v4, v4, v5
	v_mov_b32_e32 v6, v1
	v_pk_mul_f32 v[0:1], v[12:13], v[6:7]
	v_add_f32_e32 v5, 1.0, v8
	v_rcp_f32_e32 v13, v5
	v_mul_f32_e32 v5, 0xbfb8aa3b, v11
	v_exp_f32_e32 v5, v5
	v_mov_b32_e32 v8, v2
	v_mul_f32_e32 v6, v0, v1
	v_pk_mul_f32 v[0:1], v[12:13], v[8:9]
	v_add_f32_e32 v2, 1.0, v5
	v_rcp_f32_e32 v13, v2
	v_cvt_pk_bf16_f32 v2, v4, v6
	v_mul_f32_e32 v4, v0, v1
	v_pk_mul_f32 v[0:1], v[12:13], v[10:11]
	s_nop 0
	v_mul_f32_e32 v0, v0, v1
	v_cvt_pk_bf16_f32 v3, v4, v0
	global_store_dwordx2 v[18:19], v[2:3], off offset:96

.LBB0_497:
	s_or_b64 exec, exec, s[56:57]
	s_waitcnt lgkmcnt(0)
	s_barrier
	s_and_saveexec_b64 s[0:1], s[38:39]
	s_cbranch_execz .LBB0_325
	s_mov_b64 s[20:21], src_shared_base
	s_cmp_lg_u32 s24, -1
	s_cselect_b32 s2, s24, 0
	s_cselect_b32 s20, s21, 0
	v_mov_b32_e32 v0, s2
	v_mov_b32_e32 v1, s20
	s_waitcnt vmcnt(0)
	flat_store_dword v[0:1], v205 sc0 sc1
	s_waitcnt vmcnt(0)
	s_branch .LBB0_325
